# MLA prep: rotary-part q/k loads widened dwordx2 pairs -> dwordx4 + DPP exchange
# baseline (speedup 1.0000x reference)
; __global__ void __launch_bounds__(512, 2) mega_fwd(Args args) {
;     ...
;             if (gw < T) MLAP_LOAD(gw);
;             for (int m = gw; m < T; m += NGW) {
;                 bf16_t* qp = Qb + (size_t)m * 1536 + hh * 192; bf16_t* kp = Kb + (size_t)m * 1536 + hh * 192;
;                 const u32x4 qa0 = nqa0, qa1 = nqa1, ka0 = nka0, ka1 = nka1; const u32x2 qr1 = nqr1, qr2 = nqr2, kr1 = nkr1, kr2 = nkr2;
;                 const float pos = (float)npos;
;                 if (m + NGW < T) MLAP_LOAD(m + NGW);
.LBB0_986:
	s_waitcnt vmcnt(0)
	v_mov_b64_e32 v[48:49], v[72:73]
	v_mov_b64_e32 v[52:53], v[76:77]
	s_waitcnt vmcnt(0)
	v_mov_b64_e32 v[56:57], v[64:65]
	v_mov_b64_e32 v[60:61], v[68:69]
	v_mov_b64_e32 v[50:51], v[74:75]
	v_mov_b64_e32 v[54:55], v[78:79]
	v_mov_b64_e32 v[58:59], v[66:67]
	v_mov_b64_e32 v[62:63], v[70:71]
	v_mov_b64_e32 v[108:109], v[140:141]
	v_mov_b64_e32 v[110:111], v[138:139]
	s_waitcnt vmcnt(0)
	v_mov_b64_e32 v[112:113], v[132:133]
	s_waitcnt vmcnt(0)
	v_mov_b64_e32 v[118:119], v[128:129]
	s_waitcnt vmcnt(0)
	v_mov_b32_e32 v147, v126

; __global__ void __launch_bounds__(512, 2) mega_fwd(Args args) {
;     ...
;             const float* gqn = args.in[13]; const float* gkn = args.in[14];
;             f32x4 gq[4], gk[4];
; #pragma unroll
;             for (int i = 0; i < 4; ++i) { gq[i] = *(const f32x4*)(gqn + 16 * jj + 4 * i); gk[i] = *(const f32x4*)(gkn + 16 * jj + 4 * i); }
;             const f32x4 gq1 = *(const f32x4*)(gqn + 128 + 4 * jj), gq2 = *(const f32x4*)(gqn + 160 + 4 * jj), gk1 = *(const f32x4*)(gkn + 128 + 4 * jj), gk2 = *(const f32x4*)(gkn + 160 + 4 * jj);
;             float ifr[4];
; #pragma unroll
;             for (int e = 0; e < 4; ++e) ifr[e] = exp2f(-(float)(4 * jj + e) * (13.287712379549449f / 32.f));
;             const float qsc = 0.07216878364870322f * LOG2E;
;             u32x4 nqa0, nqa1, nka0, nka1; u32x2 nqr1, nqr2, nkr1, nkr2; int npos;
;     ...
;             if (gw < T) MLAP_LOAD(gw);
;             for (int m = gw; m < T; m += NGW) {
;                 bf16_t* qp = Qb + (size_t)m * 1536 + hh * 192; bf16_t* kp = Kb + (size_t)m * 1536 + hh * 192;
;                 const u32x4 qa0 = nqa0, qa1 = nqa1, ka0 = nka0, ka1 = nka1; const u32x2 qr1 = nqr1, qr2 = nqr2, kr1 = nkr1, kr2 = nkr2;
;                 const float pos = (float)npos;
;                 if (m + NGW < T) MLAP_LOAD(m + NGW);
.LBB0_988:
	global_load_dwordx4 v[0:3], v[82:83], off offset:48
	global_load_dwordx4 v[4:7], v[82:83], off offset:32
	global_load_dwordx4 v[8:11], v[82:83], off offset:16
	global_load_dwordx4 v[12:15], v[82:83], off
	global_load_dwordx4 v[16:19], v[84:85], off offset:48
	global_load_dwordx4 v[20:23], v[84:85], off offset:32
	global_load_dwordx4 v[24:27], v[84:85], off offset:16
	global_load_dwordx4 v[28:31], v[84:85], off
	global_load_dwordx4 v[32:35], v[86:87], off offset:512
	global_load_dwordx4 v[36:39], v[86:87], off offset:640
	global_load_dwordx4 v[40:43], v[88:89], off offset:512
	global_load_dwordx4 v[44:47], v[88:89], off offset:640
	s_waitcnt vmcnt(23)
	v_mov_b64_e32 v[70:71], v[62:63]
	v_mov_b64_e32 v[66:67], v[58:59]
	v_mov_b64_e32 v[78:79], v[54:55]
	v_mov_b64_e32 v[74:75], v[50:51]
	v_cmp_ne_u32_e64 s[0:1], 1, v146
	s_andn2_b64 vcc, exec, s[2:3]
	s_waitcnt vmcnt(20)
	v_mov_b32_e32 v126, v147
	v_mov_b64_e32 v[128:129], v[118:119]
	v_mov_b64_e32 v[132:133], v[112:113]
	v_mov_b64_e32 v[138:139], v[110:111]
	v_mov_b64_e32 v[140:141], v[108:109]
	v_mov_b64_e32 v[68:69], v[60:61]
	v_mov_b64_e32 v[64:65], v[56:57]
	v_mov_b64_e32 v[76:77], v[52:53]
	v_mov_b64_e32 v[72:73], v[48:49]
	s_cbranch_vccnz .LBB0_990
	global_load_dwordx4 v[76:79], v[90:91], off offset:16
	global_load_dwordx4 v[72:75], v[90:91], off
	v_lshl_add_u64 v[220:221], v[92:93], 0, v[240:241]
	global_load_dwordx4 v[212:215], v[220:221], off offset:256
	s_nop 0
	global_load_dwordx4 v[68:71], v[94:95], off offset:16
	global_load_dwordx4 v[64:67], v[94:95], off
	v_lshl_add_u64 v[222:223], v[96:97], 0, v[240:241]
	global_load_dwordx4 v[216:219], v[222:223], off offset:1536
	s_nop 0
	global_load_dword v126, v81, s[22:23]
.LBB0_990:
	s_and_b64 vcc, exec, s[0:1]
	s_cbranch_vccnz .LBB0_986
	s_waitcnt vmcnt(0)
	v_mov_b32_dpp v248, v212 quad_perm:[1,0,3,2] row_mask:0xf bank_mask:0xf
	v_mov_b32_dpp v249, v213 quad_perm:[1,0,3,2] row_mask:0xf bank_mask:0xf
	v_mov_b32_dpp v250, v214 quad_perm:[1,0,3,2] row_mask:0xf bank_mask:0xf
	v_mov_b32_dpp v251, v215 quad_perm:[1,0,3,2] row_mask:0xf bank_mask:0xf
	v_cndmask_b32_e64 v140, v212, v250, s[94:95]
	v_cndmask_b32_e64 v141, v213, v251, s[94:95]
	v_cndmask_b32_e64 v138, v248, v214, s[94:95]
	v_cndmask_b32_e64 v139, v249, v215, s[94:95]
	v_mov_b32_dpp v248, v216 quad_perm:[1,0,3,2] row_mask:0xf bank_mask:0xf
	v_mov_b32_dpp v249, v217 quad_perm:[1,0,3,2] row_mask:0xf bank_mask:0xf
	v_mov_b32_dpp v250, v218 quad_perm:[1,0,3,2] row_mask:0xf bank_mask:0xf
	v_mov_b32_dpp v251, v219 quad_perm:[1,0,3,2] row_mask:0xf bank_mask:0xf
	v_cndmask_b32_e64 v132, v216, v250, s[94:95]
	v_cndmask_b32_e64 v133, v217, v251, s[94:95]
	v_cndmask_b32_e64 v128, v248, v218, s[94:95]
	v_cndmask_b32_e64 v129, v249, v219, s[94:95]
	v_mov_b64_e32 v[60:61], v[68:69]
	s_waitcnt vmcnt(0)
	v_mov_b64_e32 v[56:57], v[64:65]
	v_mov_b64_e32 v[52:53], v[76:77]
	v_mov_b64_e32 v[48:49], v[72:73]
	v_mov_b64_e32 v[114:115], v[106:107]
	v_mov_b64_e32 v[116:117], v[104:105]
	v_mov_b64_e32 v[120:121], v[102:103]
	v_mov_b64_e32 v[122:123], v[100:101]
	v_mov_b64_e32 v[124:125], v[98:99]
	s_mov_b64 s[50:51], s[24:25]
	s_mov_b32 s34, s82
	s_waitcnt vmcnt(0)
	v_mov_b32_e32 v147, v126
	v_mov_b64_e32 v[118:119], v[128:129]
	v_mov_b64_e32 v[112:113], v[132:133]
	v_mov_b64_e32 v[110:111], v[138:139]
	v_mov_b64_e32 v[108:109], v[140:141]
	v_mov_b64_e32 v[62:63], v[70:71]
	v_mov_b64_e32 v[58:59], v[66:67]
	v_mov_b64_e32 v[54:55], v[78:79]
	v_mov_b64_e32 v[50:51], v[74:75]
.LBB0_992:
	s_add_i32 s34, s34, s96
	s_cmpk_gt_i32 s34, 0x3fff
	s_cselect_b64 s[52:53], -1, 0
	s_and_b64 vcc, exec, s[52:53]
	s_cbranch_vccnz .LBB0_994
	v_lshl_add_u64 v[56:57], s[86:87], 0, v[122:123]
	v_add_co_u32_e32 v48, vcc, 0x15800000, v56
	v_lshl_add_u64 v[58:59], s[86:87], 0, v[120:121]
	s_nop 0
	v_addc_co_u32_e32 v49, vcc, 0, v57, vcc
	v_add_co_u32_e32 v58, vcc, 0x15800000, v58
	v_lshl_add_u64 v[52:53], v[56:57], 0, s[42:43]
	s_nop 0
	v_addc_co_u32_e32 v59, vcc, 0, v59, vcc
	v_lshl_add_u64 v[60:61], v[56:57], 0, s[44:45]
	v_add_co_u32_e32 v56, vcc, 0x18800000, v56
	v_lshl_add_u64 v[112:113], s[86:87], 0, v[124:125]
	s_nop 0
	v_addc_co_u32_e32 v57, vcc, 0, v57, vcc
	v_add_co_u32_e32 v118, vcc, 0xa800000, v112
	global_load_dwordx4 v[48:51], v[48:49], off
	s_nop 0
	global_load_dwordx4 v[52:55], v[52:53], off offset:16
	v_addc_co_u32_e32 v119, vcc, 0, v113, vcc
	v_lshl_add_u64 v[220:221], v[58:59], 0, v[240:241]
	global_load_dwordx4 v[212:215], v[220:221], off offset:256
	s_nop 0
	global_load_dwordx4 v[56:59], v[56:57], off
	s_nop 0
	global_load_dwordx4 v[60:63], v[60:61], off offset:16
	s_nop 0
	v_lshl_add_u64 v[222:223], v[118:119], 0, v[240:241]
	global_load_dwordx4 v[216:219], v[222:223], off offset:1536
	s_nop 0
	s_nop 0
	s_nop 0
	global_load_dword v147, v81, s[50:51]
; __global__ void __launch_bounds__(512, 2) mega_fwd(Args args) {
;     ...
;                 const float pos = (float)npos;
;                 if (m + NGW < T) MLAP_LOAD(m + NGW);
;                 float cs[4], sn[4];
; #pragma unroll
;                 for (int e = 0; e < 4; ++e) { const float ang = pos * ifr[e]; double rv = (double)ang * 0.15915494309189535; rv -= rint(rv); const float rf = (float)rv; cs[e] = __builtin_amdgcn_cosf(rf); sn[e] = __builtin_amdgcn_sinf(rf); }
.LBB0_994:
	v_cvt_f32_i32_e32 v148, v126
	v_and_b32_e32 v171, 0xffff0000, v72
	v_and_b32_e32 v195, 0xffff0000, v64
	v_lshlrev_b32_e32 v170, 16, v72
	v_mul_f32_e32 v130, v143, v148
	v_mul_f32_e32 v126, v142, v148
	v_cvt_f64_f32_e32 v[134:135], v130
	v_cvt_f64_f32_e32 v[126:127], v126
	v_mul_f64 v[136:137], v[134:135], s[46:47]
	v_mul_f64 v[130:131], v[126:127], s[46:47]
	v_rndne_f64_e32 v[136:137], v[136:137]
	v_lshlrev_b32_e32 v194, 16, v64
	v_mov_b32_e32 v196, v195
	v_mov_b32_e32 v197, v171
	v_rndne_f64_e32 v[130:131], v[130:131]
	v_fma_f64 v[134:135], v[134:135], s[46:47], -v[136:137]
	v_lshlrev_b32_e32 v168, 16, v73
	v_lshlrev_b32_e32 v182, 16, v69
	v_and_b32_e32 v183, 0xffff0000, v69
	v_lshlrev_b32_e32 v186, 16, v68
	v_and_b32_e32 v187, 0xffff0000, v68
	v_lshlrev_b32_e32 v192, 16, v65
	v_mov_b32_e32 v68, v194
	v_mov_b32_e32 v69, v170
	v_pk_mul_f32 v[196:197], v[196:197], v[196:197]
	v_fma_f64 v[126:127], v[126:127], s[46:47], -v[130:131]
	v_cvt_f32_f64_e32 v131, v[134:135]
	v_mul_f32_e32 v134, v144, v148
	v_and_b32_e32 v169, 0xffff0000, v73
	v_and_b32_e32 v193, 0xffff0000, v65
	v_mov_b32_e32 v64, v192
	v_mov_b32_e32 v65, v168
	v_pk_fma_f32 v[68:69], v[68:69], v[68:69], v[196:197]
	v_cvt_f64_f32_e32 v[134:135], v134
	v_lshlrev_b32_e32 v166, 16, v74
	v_lshlrev_b32_e32 v188, 16, v67
	v_and_b32_e32 v189, 0xffff0000, v67
	v_lshlrev_b32_e32 v190, 16, v66
	v_and_b32_e32 v191, 0xffff0000, v66
	v_mov_b32_e32 v66, v193
	v_mov_b32_e32 v67, v169
	v_pk_fma_f32 v[64:65], v[64:65], v[64:65], v[68:69]
	v_mul_f64 v[136:137], v[134:135], s[46:47]
	v_and_b32_e32 v167, 0xffff0000, v74
	v_mov_b32_e32 v206, v190
	v_mov_b32_e32 v207, v166
	v_pk_fma_f32 v[64:65], v[66:67], v[66:67], v[64:65]
	v_rndne_f64_e32 v[136:137], v[136:137]
	v_lshlrev_b32_e32 v164, 16, v76
	v_and_b32_e32 v165, 0xffff0000, v76
	v_lshlrev_b32_e32 v76, 16, v75
	v_mov_b32_e32 v208, v191
	v_mov_b32_e32 v209, v167
	v_pk_fma_f32 v[64:65], v[206:207], v[206:207], v[64:65]
	v_fma_f64 v[134:135], v[134:135], s[46:47], -v[136:137]
	v_lshlrev_b32_e32 v162, 16, v77
	v_and_b32_e32 v163, 0xffff0000, v77
	v_and_b32_e32 v77, 0xffff0000, v75
	v_mov_b32_e32 v202, v188
	v_mov_b32_e32 v203, v76
	v_pk_fma_f32 v[64:65], v[208:209], v[208:209], v[64:65]
	v_cvt_f32_f64_e32 v135, v[134:135]
	v_mov_b32_e32 v204, v189
	v_mov_b32_e32 v205, v77
	v_pk_fma_f32 v[64:65], v[202:203], v[202:203], v[64:65]
	v_cos_f32_e32 v134, v135
	v_sin_f32_e32 v136, v135
	v_mul_f32_e32 v135, v145, v148
	v_mov_b32_e32 v198, v186
	v_mov_b32_e32 v199, v164
	v_pk_fma_f32 v[64:65], v[204:205], v[204:205], v[64:65]
	v_cvt_f64_f32_e32 v[148:149], v135
	v_mov_b32_e32 v200, v187
	v_mov_b32_e32 v201, v165
	v_pk_fma_f32 v[64:65], v[198:199], v[198:199], v[64:65]
	v_mul_f64 v[150:151], v[148:149], s[46:47]
	v_lshlrev_b32_e32 v160, 16, v78
	v_and_b32_e32 v161, 0xffff0000, v78
	v_lshlrev_b32_e32 v180, 16, v70
	v_and_b32_e32 v181, 0xffff0000, v70
	v_mov_b32_e32 v68, v182
	v_mov_b32_e32 v69, v162
	v_pk_fma_f32 v[64:65], v[200:201], v[200:201], v[64:65]
	v_rndne_f64_e32 v[150:151], v[150:151]
	v_lshlrev_b32_e32 v156, 16, v79
	v_and_b32_e32 v157, 0xffff0000, v79
	v_pk_mul_f32 v[78:79], v[160:161], v[160:161]
	v_lshlrev_b32_e32 v176, 16, v71
	v_and_b32_e32 v177, 0xffff0000, v71
	v_pk_mul_f32 v[70:71], v[180:181], v[180:181]
	v_mov_b32_e32 v196, v183
	v_mov_b32_e32 v197, v163
	v_pk_fma_f32 v[64:65], v[68:69], v[68:69], v[64:65]
	v_fma_f64 v[148:149], v[148:149], s[46:47], -v[150:151]
	v_pk_fma_f32 v[64:65], v[196:197], v[196:197], v[64:65]
	v_mov_b32_e32 v66, v70
	v_mov_b32_e32 v67, v78
	v_cvt_f32_f64_e32 v137, v[148:149]
	v_lshlrev_b32_e32 v148, 16, v141
	v_and_b32_e32 v149, 0xffff0000, v141
	v_lshlrev_b32_e32 v154, 16, v140
	v_and_b32_e32 v155, 0xffff0000, v140
	v_lshlrev_b32_e32 v140, 16, v138
	v_and_b32_e32 v141, 0xffff0000, v138
	v_pk_mul_f32 v[158:159], v[156:157], v[156:157]
	v_lshlrev_b32_e32 v72, 16, v133
	v_and_b32_e32 v73, 0xffff0000, v133
	v_lshlrev_b32_e32 v174, 16, v132
	v_and_b32_e32 v175, 0xffff0000, v132
	v_lshlrev_b32_e32 v132, 16, v128
	v_and_b32_e32 v133, 0xffff0000, v128
	v_pk_mul_f32 v[178:179], v[176:177], v[176:177]
	v_pk_add_f32 v[64:65], v[64:65], v[66:67]
	v_mov_b32_e32 v78, v71
	v_lshlrev_b32_e32 v150, 16, v139
	v_and_b32_e32 v151, 0xffff0000, v139
	v_pk_mul_f32 v[138:139], v[140:141], v[140:141]
	v_lshlrev_b32_e32 v74, 16, v129
	v_and_b32_e32 v75, 0xffff0000, v129
	v_pk_mul_f32 v[128:129], v[132:133], v[132:133]
	v_pk_add_f32 v[64:65], v[64:65], v[78:79]
	v_mov_b32_e32 v66, v178
	v_mov_b32_e32 v67, v158
	v_pk_fma_f32 v[138:139], v[154:155], v[154:155], v[138:139]
	v_pk_fma_f32 v[128:129], v[174:175], v[174:175], v[128:129]
	v_pk_add_f32 v[64:65], v[64:65], v[66:67]
	v_mov_b32_e32 v158, v179
	v_pk_mul_f32 v[152:153], v[150:151], v[150:151]
	v_pk_mul_f32 v[172:173], v[74:75], v[74:75]
	v_pk_add_f32 v[64:65], v[64:65], v[158:159]
	v_mov_b32_e32 v66, v128
	v_mov_b32_e32 v67, v138
	v_pk_fma_f32 v[152:153], v[148:149], v[148:149], v[152:153]
	v_pk_fma_f32 v[172:173], v[72:73], v[72:73], v[172:173]
	v_pk_add_f32 v[64:65], v[64:65], v[66:67]
	v_mov_b32_e32 v138, v129
	v_pk_add_f32 v[64:65], v[64:65], v[138:139]
	v_mov_b32_e32 v66, v172
	v_mov_b32_e32 v67, v152
	v_pk_add_f32 v[64:65], v[64:65], v[66:67]
	v_mov_b32_e32 v152, v173
	v_pk_add_f32 v[64:65], v[64:65], v[152:153]
	v_cvt_f32_f64_e32 v127, v[126:127]
	v_cos_f32_e32 v126, v127
	v_mov_b32_dpp v67, v65 quad_perm:[1,0,3,2] row_mask:0xf bank_mask:0xf bound_ctrl:1
	v_mov_b32_dpp v66, v64 quad_perm:[1,0,3,2] row_mask:0xf bank_mask:0xf bound_ctrl:1
	v_pk_add_f32 v[64:65], v[64:65], v[66:67]
	v_sin_f32_e32 v130, v127
	v_cos_f32_e32 v127, v131
	v_mov_b32_dpp v67, v65 quad_perm:[2,3,0,1] row_mask:0xf bank_mask:0xf bound_ctrl:1
	v_mov_b32_dpp v66, v64 quad_perm:[2,3,0,1] row_mask:0xf bank_mask:0xf bound_ctrl:1
	v_pk_add_f32 v[64:65], v[64:65], v[66:67]
	v_sin_f32_e32 v131, v131
	v_cos_f32_e32 v135, v137
	v_mov_b32_dpp v67, v65 row_half_mirror row_mask:0xf bank_mask:0xf bound_ctrl:1
	v_mov_b32_dpp v66, v64 row_half_mirror row_mask:0xf bank_mask:0xf bound_ctrl:1
	v_pk_add_f32 v[64:65], v[64:65], v[66:67]
	v_sin_f32_e32 v137, v137
	v_pk_fma_f32 v[78:79], v[64:65], s[48:49], v[80:81] op_sel_hi:[1,0,0]
	v_lshl_add_u64 v[128:129], s[86:87], 0, v[116:117]
	v_mul_f32_e32 v64, 0x4b800000, v79
	v_cmp_gt_f32_e32 vcc, s33, v79
	v_lshl_add_u64 v[138:139], s[86:87], 0, v[114:115]
	s_add_u32 s50, s50, s26
	v_cndmask_b32_e32 v64, v79, v64, vcc
	v_rsq_f32_e32 v64, v64
	s_addc_u32 s51, s51, s27
	v_lshl_add_u64 v[124:125], v[124:125], 0, s[28:29]
	v_lshl_add_u64 v[122:123], v[122:123], 0, s[36:37]
	v_mul_f32_e32 v65, 0x45800000, v64
	v_cndmask_b32_e32 v64, v64, v65, vcc
	v_mul_f32_e32 v152, 0x3dd53b94, v64
	v_pk_mul_f32 v[64:65], v[152:153], v[170:171] op_sel_hi:[0,1]
	v_pk_mul_f32 v[66:67], v[152:153], v[168:169] op_sel_hi:[0,1]
	v_pk_mul_f32 v[64:65], v[12:13], v[64:65]
	v_pk_mul_f32 v[66:67], v[14:15], v[66:67]
	v_cvt_pk_bf16_f32 v64, v64, v65
	v_cvt_pk_bf16_f32 v65, v66, v67
	v_pk_mul_f32 v[66:67], v[152:153], v[166:167] op_sel_hi:[0,1]
	v_pk_mul_f32 v[68:69], v[152:153], v[76:77] op_sel_hi:[0,1]
	v_pk_mul_f32 v[66:67], v[8:9], v[66:67]
	v_pk_mul_f32 v[68:69], v[10:11], v[68:69]
	v_cvt_pk_bf16_f32 v66, v66, v67
	v_cvt_pk_bf16_f32 v67, v68, v69
	v_pk_mul_f32 v[68:69], v[152:153], v[164:165] op_sel_hi:[0,1]
	v_pk_mul_f32 v[70:71], v[152:153], v[162:163] op_sel_hi:[0,1]
	v_pk_mul_f32 v[68:69], v[4:5], v[68:69]
	v_pk_mul_f32 v[70:71], v[6:7], v[70:71]
	v_cvt_pk_bf16_f32 v68, v68, v69
	v_cvt_pk_bf16_f32 v69, v70, v71
	v_pk_mul_f32 v[70:71], v[152:153], v[160:161] op_sel_hi:[0,1]
	v_pk_mul_f32 v[76:77], v[152:153], v[156:157] op_sel_hi:[0,1]
	v_pk_mul_f32 v[70:71], v[0:1], v[70:71]
	v_pk_mul_f32 v[76:77], v[2:3], v[76:77]
	v_pk_mul_f32 v[140:141], v[152:153], v[140:141] op_sel_hi:[0,1]
	v_cvt_pk_bf16_f32 v70, v70, v71
	v_cvt_pk_bf16_f32 v71, v76, v77
	v_pk_mul_f32 v[76:77], v[152:153], v[154:155] op_sel_hi:[0,1]
	v_pk_mul_f32 v[140:141], v[36:37], v[140:141]
	v_pk_mul_f32 v[76:77], v[32:33], v[76:77]
	v_pk_mul_f32 v[154:155], v[140:141], v[130:131]
	v_lshl_add_u64 v[120:121], v[120:121], 0, s[36:37]
	v_pk_fma_f32 v[154:155], v[76:77], v[126:127], v[154:155] neg_lo:[0,0,1] neg_hi:[0,0,1]
	v_pk_mul_f32 v[76:77], v[76:77], v[130:131]
	v_lshl_add_u64 v[116:117], v[116:117], 0, s[36:37]
	v_pk_fma_f32 v[76:77], v[126:127], v[140:141], v[76:77]
	v_pk_mul_f32 v[140:141], v[152:153], v[148:149] op_sel_hi:[0,1]
	v_pk_mul_f32 v[148:149], v[152:153], v[150:151] op_sel_hi:[0,1]
	v_pk_mul_f32 v[148:149], v[38:39], v[148:149]
	v_pk_mul_f32 v[140:141], v[34:35], v[140:141]
	v_pk_mul_f32 v[150:151], v[148:149], v[136:137]
	v_cvt_pk_bf16_f32 v76, v76, v77
	v_pk_fma_f32 v[150:151], v[140:141], v[134:135], v[150:151] neg_lo:[0,0,1] neg_hi:[0,0,1]
	v_pk_mul_f32 v[140:141], v[140:141], v[136:137]
	v_lshl_add_u64 v[114:115], v[114:115], 0, s[36:37]
	v_pk_fma_f32 v[140:141], v[134:135], v[148:149], v[140:141]
	v_cvt_pk_bf16_f32 v148, v154, v155
	v_cvt_pk_bf16_f32 v77, v140, v141
	v_add_co_u32_e32 v140, vcc, s16, v128
	v_cvt_pk_bf16_f32 v149, v150, v151
	s_nop 0
	v_addc_co_u32_e32 v141, vcc, 0, v129, vcc
	global_store_dwordx4 v[140:141], v[64:67], off
	global_store_dwordx4 v[140:141], v[68:71], off offset:16
	v_cmp_gt_f32_e32 vcc, s33, v78
	v_mul_f32_e32 v64, 0x4b800000, v78
	s_nop 0
	v_cndmask_b32_e32 v64, v78, v64, vcc
	v_rsq_f32_e32 v66, v64
	v_add_co_u32_e64 v64, s[0:1], s16, v138
	s_nop 1
	v_addc_co_u32_e64 v65, s[0:1], 0, v139, s[0:1]
	s_nop 1
	v_mov_b32_dpp v248, v148 quad_perm:[1,0,3,2] row_mask:0xf bank_mask:0xf
	v_mov_b32_dpp v249, v149 quad_perm:[1,0,3,2] row_mask:0xf bank_mask:0xf
	v_mov_b32_dpp v250, v76 quad_perm:[1,0,3,2] row_mask:0xf bank_mask:0xf
	v_mov_b32_dpp v251, v77 quad_perm:[1,0,3,2] row_mask:0xf bank_mask:0xf
	v_cndmask_b32_e64 v244, v148, v250, s[94:95]
	v_cndmask_b32_e64 v245, v149, v251, s[94:95]
	v_cndmask_b32_e64 v246, v248, v76, s[94:95]
	v_cndmask_b32_e64 v247, v249, v77, s[94:95]
	v_lshl_add_u64 v[64:65], v[64:65], 0, v[240:241]
	global_store_dwordx4 v[64:65], v[244:247], off offset:256
; __global__ void __launch_bounds__(512, 2) mega_fwd(Args args) {
;     ...
;             if (gw < T) MLAP_LOAD(gw);
;             for (int m = gw; m < T; m += NGW) {
;                 bf16_t* qp = Qb + (size_t)m * 1536 + hh * 192; bf16_t* kp = Kb + (size_t)m * 1536 + hh * 192;
;                 const u32x4 qa0 = nqa0, qa1 = nqa1, ka0 = nka0, ka1 = nka1; const u32x2 qr1 = nqr1, qr2 = nqr2, kr1 = nkr1, kr2 = nkr2;
;                 const float pos = (float)npos;
;                 if (m + NGW < T) MLAP_LOAD(m + NGW);
;     ...
;                 MLAP_ONE(qa0, qa1, qr1, qr2, gq, gq1, gq2, qsc, qp);
;                 MLAP_ONE(ka0, ka1, kr1, kr2, gk, gk1, gk2, 1.f, kp);
	v_mul_f32_e32 v64, 0x45800000, v66
	v_cndmask_b32_e32 v76, v66, v64, vcc
	v_pk_mul_f32 v[64:65], v[76:77], v[194:195] op_sel_hi:[0,1]
	v_pk_mul_f32 v[66:67], v[76:77], v[192:193] op_sel_hi:[0,1]
	v_pk_mul_f32 v[64:65], v[28:29], v[64:65]
	v_pk_mul_f32 v[66:67], v[30:31], v[66:67]
	v_cvt_pk_bf16_f32 v64, v64, v65
	v_cvt_pk_bf16_f32 v65, v66, v67
	v_pk_mul_f32 v[66:67], v[76:77], v[190:191] op_sel_hi:[0,1]
	v_pk_mul_f32 v[68:69], v[76:77], v[188:189] op_sel_hi:[0,1]
	v_pk_mul_f32 v[66:67], v[24:25], v[66:67]
	v_pk_mul_f32 v[68:69], v[26:27], v[68:69]
	v_cvt_pk_bf16_f32 v66, v66, v67
	v_cvt_pk_bf16_f32 v67, v68, v69
	v_pk_mul_f32 v[68:69], v[76:77], v[186:187] op_sel_hi:[0,1]
	v_pk_mul_f32 v[70:71], v[76:77], v[182:183] op_sel_hi:[0,1]
	v_pk_mul_f32 v[68:69], v[20:21], v[68:69]
	v_pk_mul_f32 v[70:71], v[22:23], v[70:71]
	v_cvt_pk_bf16_f32 v68, v68, v69
	v_cvt_pk_bf16_f32 v69, v70, v71
	v_pk_mul_f32 v[70:71], v[76:77], v[180:181] op_sel_hi:[0,1]
	v_pk_mul_f32 v[78:79], v[76:77], v[176:177] op_sel_hi:[0,1]
	v_pk_mul_f32 v[74:75], v[76:77], v[74:75] op_sel_hi:[0,1]
	v_pk_mul_f32 v[70:71], v[16:17], v[70:71]
	v_pk_mul_f32 v[78:79], v[18:19], v[78:79]
	v_pk_mul_f32 v[72:73], v[76:77], v[72:73] op_sel_hi:[0,1]
	v_pk_mul_f32 v[74:75], v[46:47], v[74:75]
	v_cvt_pk_bf16_f32 v70, v70, v71
	v_cvt_pk_bf16_f32 v71, v78, v79
	v_pk_mul_f32 v[78:79], v[76:77], v[174:175] op_sel_hi:[0,1]
	v_pk_mul_f32 v[132:133], v[76:77], v[132:133] op_sel_hi:[0,1]
	v_pk_mul_f32 v[72:73], v[42:43], v[72:73]
	v_pk_mul_f32 v[76:77], v[74:75], v[136:137]
	v_pk_mul_f32 v[132:133], v[44:45], v[132:133]
	v_pk_fma_f32 v[76:77], v[72:73], v[134:135], v[76:77] neg_lo:[0,0,1] neg_hi:[0,0,1]
	v_pk_mul_f32 v[72:73], v[72:73], v[136:137]
	v_pk_mul_f32 v[78:79], v[40:41], v[78:79]
	v_pk_fma_f32 v[72:73], v[134:135], v[74:75], v[72:73]
	v_cvt_pk_bf16_f32 v75, v76, v77
	v_cvt_pk_bf16_f32 v77, v72, v73
	v_add_co_u32_e32 v72, vcc, s17, v128
	v_pk_mul_f32 v[140:141], v[132:133], v[130:131]
	s_nop 0
	v_addc_co_u32_e32 v73, vcc, 0, v129, vcc
	global_store_dwordx4 v[72:73], v[64:67], off
	global_store_dwordx4 v[72:73], v[68:71], off offset:16
	v_pk_fma_f32 v[140:141], v[78:79], v[126:127], v[140:141] neg_lo:[0,0,1] neg_hi:[0,0,1]
	v_add_co_u32_e32 v64, vcc, s17, v138
	v_pk_mul_f32 v[78:79], v[78:79], v[130:131]
	s_nop 0
	v_addc_co_u32_e32 v65, vcc, 0, v139, vcc
	v_pk_fma_f32 v[78:79], v[126:127], v[132:133], v[78:79]
	v_cvt_pk_bf16_f32 v74, v140, v141
	s_and_b64 vcc, exec, s[52:53]
	v_cvt_pk_bf16_f32 v76, v78, v79
	s_nop 1
	v_mov_b32_dpp v248, v74 quad_perm:[1,0,3,2] row_mask:0xf bank_mask:0xf
	v_mov_b32_dpp v249, v75 quad_perm:[1,0,3,2] row_mask:0xf bank_mask:0xf
	v_mov_b32_dpp v250, v76 quad_perm:[1,0,3,2] row_mask:0xf bank_mask:0xf
	v_mov_b32_dpp v251, v77 quad_perm:[1,0,3,2] row_mask:0xf bank_mask:0xf
	v_cndmask_b32_e64 v244, v74, v250, s[94:95]
	v_cndmask_b32_e64 v245, v75, v251, s[94:95]
	v_cndmask_b32_e64 v246, v248, v76, s[94:95]
	v_cndmask_b32_e64 v247, v249, v77, s[94:95]
	v_lshl_add_u64 v[64:65], v[64:65], 0, v[240:241]
	global_store_dwordx4 v[64:65], v[244:247], off offset:256
	s_cbranch_vccnz .LBB0_987
	s_waitcnt vmcnt(6)
	v_mov_b64_e32 v[74:75], v[50:51]
	v_mov_b64_e32 v[78:79], v[54:55]
	v_mov_b64_e32 v[66:67], v[58:59]
	v_mov_b64_e32 v[70:71], v[62:63]
	v_mov_b64_e32 v[72:73], v[48:49]
	v_mov_b64_e32 v[76:77], v[52:53]
	v_mov_b64_e32 v[64:65], v[56:57]
	v_mov_b64_e32 v[68:69], v[60:61]
	v_mov_b32_e32 v126, v147
	v_mov_b32_dpp v248, v212 quad_perm:[1,0,3,2] row_mask:0xf bank_mask:0xf
	v_mov_b32_dpp v249, v213 quad_perm:[1,0,3,2] row_mask:0xf bank_mask:0xf
	v_mov_b32_dpp v250, v214 quad_perm:[1,0,3,2] row_mask:0xf bank_mask:0xf
	v_mov_b32_dpp v251, v215 quad_perm:[1,0,3,2] row_mask:0xf bank_mask:0xf
	v_cndmask_b32_e64 v140, v212, v250, s[94:95]
	v_cndmask_b32_e64 v141, v213, v251, s[94:95]
	v_cndmask_b32_e64 v138, v248, v214, s[94:95]
	v_cndmask_b32_e64 v139, v249, v215, s[94:95]
	v_mov_b32_dpp v248, v216 quad_perm:[1,0,3,2] row_mask:0xf bank_mask:0xf
	v_mov_b32_dpp v249, v217 quad_perm:[1,0,3,2] row_mask:0xf bank_mask:0xf
	v_mov_b32_dpp v250, v218 quad_perm:[1,0,3,2] row_mask:0xf bank_mask:0xf
	v_mov_b32_dpp v251, v219 quad_perm:[1,0,3,2] row_mask:0xf bank_mask:0xf
	v_cndmask_b32_e64 v132, v216, v250, s[94:95]
	v_cndmask_b32_e64 v133, v217, v251, s[94:95]
	v_cndmask_b32_e64 v128, v248, v218, s[94:95]
	v_cndmask_b32_e64 v129, v249, v219, s[94:95]
	s_branch .LBB0_992
